# thr: fourth radix sweep skips key tiles that had no key sharing the 16-bit prefix in the third sweep (per-wave tile bitmask)
# speedup vs baseline: 1.0023x; 1.0023x over previous
; DI void dsa_thr_item(const Params& p, int b, int qblk, char* smem) {
;     ...
;   for (int pass = 0; pass < 4; ++pass) {
;     for (int i = tid; i < 8192; i += 512) hist[i] = 0u;
;     __syncthreads();
;     const int shift = 24 - 8 * pass;
;     const unsigned mypref = pref[lr];
;     const u16* kib = (const u16*)(p.ws + OFF_KIF) + (size_t)b * 128 * 1024 + lane * 8;
;     bf16x8 kn0, kn1;
;     {
;       const int kt0 = min(wave, qblk);
;       kn0 = ldg8(kib + (size_t)kt0 * 1024); kn1 = ldg8(kib + (size_t)kt0 * 1024 + 512);
;     }
;     for (int kt = wave; kt <= qblk; kt += 8) {
.LBB0_264:
	v_add_u32_e32 v1, 0x200, v1
	s_movk_i32 s0, 0x1dff
	v_cmp_lt_u32_e64 s[0:1], s0, v1
	ds_write_b32 v0, v53
	s_or_b64 s[52:53], s[0:1], s[52:53]
	v_add_u32_e32 v0, 0x800, v0
	s_andn2_b64 exec, exec, s[52:53]
	s_cbranch_execnz .LBB0_264
	s_or_b64 exec, exec, s[52:53]
	s_waitcnt lgkmcnt(0)
	s_barrier
	s_and_saveexec_b64 s[54:55], vcc
	s_cbranch_execz .LBB0_334
	global_load_dwordx4 v[36:39], v[56:57], off offset:1024
	global_load_dwordx4 v[32:35], v[56:57], off
	ds_read_b32 v94, v58 offset:32768
	ds_read_b128 v[184:187], v216 offset:33792
	ds_read_b128 v[188:191], v216 offset:33824
	ds_read_b128 v[192:195], v216 offset:33280
	ds_read_b128 v[196:199], v216 offset:33312
	ds_read_b128 v[200:203], v216 offset:33344
	ds_read_b128 v[220:223], v216 offset:33376
	ds_read_b128 v[224:227], v216 offset:33408
	ds_read_b128 v[228:231], v216 offset:33440
	ds_read_b128 v[232:235], v216 offset:33472
	ds_read_b128 v[236:239], v216 offset:33504
	ds_read_b128 v[240:243], v216 offset:33536
	ds_read_b128 v[244:247], v216 offset:33568
	ds_read_b128 v[248:251], v216 offset:33600
	s_waitcnt lgkmcnt(0)
	s_lshl_b32 s0, s72, 3
	s_sub_i32 s58, 24, s0
	s_mov_b32 s99, -1
	s_cmp_lg_u32 s72, 2
	s_cselect_b32 s98, s98, 0
	s_mov_b64 s[60:61], 0
	v_mov_b32_e32 v96, v167
	s_branch .LBB0_268

; #define MFMA(a, b, c) __builtin_amdgcn_mfma_f32_32x32x16_bf16((a), (b), (c), 0, 0, 0)
; DI f32x16 zero16() { f32x16 z; for (int i = 0; i < 16; ++i) z[i] = 0.f; return z; }
; DI void dsa_thr_item(const Params& p, int b, int qblk, char* smem) {
;     ...
;     for (int kt = wave; kt <= qblk; kt += 8) {
;       const bf16x8 k0 = kn0, k1 = kn1;
;       {
;         const int ktn = min(kt + 8, qblk);
;         kn0 = ldg8(kib + (size_t)ktn * 1024); kn1 = ldg8(kib + (size_t)ktn * 1024 + 512);
;       }
;       float sc[16];
;       {
;         f32x16 a = zero16();
;         a = MFMA(k0, *reinterpret_cast<const bf16x8*>(qil + 256), a);
;         a = MFMA(k1, *reinterpret_cast<const bf16x8*>(qil + 256 + 16), a);
; #pragma unroll
;         for (int i = 0; i < 16; ++i) sc[i] = a[i];
;       }
; #pragma unroll
;       for (int hd = 0; hd < 8; ++hd) {
;         f32x16 a = zero16();
;         a = MFMA(k0, *reinterpret_cast<const bf16x8*>(qil + hd * 32), a);
;         a = MFMA(k1, *reinterpret_cast<const bf16x8*>(qil + hd * 32 + 16), a);
;         const float wh = wq[hd];
; #pragma unroll
;         for (int i = 0; i < 16; ++i) sc[i] = fmaf(fabsf(a[i]), wh, sc[i]);
;       }
.LBB0_268:
	s_add_i32 s99, s99, 1
	v_mov_b32_e32 v97, v96
	v_add_u32_e32 v96, 8, v97
	v_min_i32_e32 v52, s71, v96
	v_lshlrev_b64 v[0:1], 11, v[52:53]
	s_waitcnt vmcnt(0)
	v_mov_b64_e32 v[42:43], v[38:39]
	s_waitcnt vmcnt(0)
	v_mov_b64_e32 v[46:47], v[34:35]
	v_lshl_add_u64 v[0:1], v[54:55], 0, v[0:1]
	v_mov_b64_e32 v[40:41], v[36:37]
	v_mov_b64_e32 v[44:45], v[32:33]
	global_load_dwordx4 v[32:35], v[0:1], off
	global_load_dwordx4 v[36:39], v[0:1], off offset:1024
	s_cmp_eq_u32 s72, 3
	s_cbranch_scc0 .Lthr_noskip
	v_readfirstlane_b32 s100, v97
	s_cmp_eq_u32 s100, s71
	s_cbranch_scc1 .Lthr_noskip
	s_bitcmp1_b32 s98, s99
	s_cbranch_scc1 .Lthr_noskip
	s_mov_b64 s[0:1], exec
	s_branch .LBB0_267
.Lthr_noskip:
	v_mfma_f32_32x32x16_bf16 v[104:119], v[44:47], v[184:187], 0
	v_mfma_f32_32x32x16_bf16 v[104:119], v[40:43], v[188:191], v[104:119]
	v_cmp_ne_u32_e64 s[0:1], s71, v97
	s_mov_b64 s[62:63], 0
	v_mfma_f32_32x32x16_bf16 v[120:135], v[44:47], v[192:195], 0
	v_mfma_f32_32x32x16_bf16 v[120:135], v[40:43], v[196:199], v[120:135]
	v_mfma_f32_32x32x16_bf16 v[136:151], v[44:47], v[200:203], 0
	v_mfma_f32_32x32x16_bf16 v[136:151], v[40:43], v[220:223], v[136:151]
	s_nop 9
	v_fma_f32 v152, |v120|, v79, v104
	v_fma_f32 v153, |v121|, v79, v105
	v_fma_f32 v154, |v122|, v79, v106
	v_fma_f32 v155, |v123|, v79, v107
	v_fma_f32 v156, |v124|, v79, v108
	v_fma_f32 v157, |v125|, v79, v109
	v_fma_f32 v158, |v126|, v79, v110
	v_fma_f32 v159, |v127|, v79, v111
	v_fma_f32 v160, |v128|, v79, v112
	v_fma_f32 v161, |v129|, v79, v113
	v_fma_f32 v98, |v130|, v79, v114
	v_fma_f32 v99, |v131|, v79, v115
	v_fma_f32 v100, |v132|, v79, v116
	v_fma_f32 v101, |v133|, v79, v117
	v_fma_f32 v102, |v134|, v79, v118
	v_fma_f32 v103, |v135|, v79, v119
	v_mfma_f32_32x32x16_bf16 v[104:119], v[44:47], v[224:227], 0
	v_mfma_f32_32x32x16_bf16 v[104:119], v[40:43], v[228:231], v[104:119]
	v_fma_f32 v152, |v136|, v80, v152
	v_fma_f32 v153, |v137|, v80, v153
	v_fma_f32 v154, |v138|, v80, v154
	v_fma_f32 v155, |v139|, v80, v155
	v_fma_f32 v156, |v140|, v80, v156
	v_fma_f32 v157, |v141|, v80, v157
	v_fma_f32 v158, |v142|, v80, v158
	v_fma_f32 v159, |v143|, v80, v159
	v_fma_f32 v160, |v144|, v80, v160
	v_fma_f32 v161, |v145|, v80, v161
	v_fma_f32 v98, |v146|, v80, v98
	v_fma_f32 v99, |v147|, v80, v99
	v_fma_f32 v100, |v148|, v80, v100
	v_fma_f32 v101, |v149|, v80, v101
	v_fma_f32 v102, |v150|, v80, v102
	v_fma_f32 v103, |v151|, v80, v103
	v_mfma_f32_32x32x16_bf16 v[120:135], v[44:47], v[232:235], 0
	v_mfma_f32_32x32x16_bf16 v[120:135], v[40:43], v[236:239], v[120:135]
	v_fma_f32 v152, |v104|, v81, v152
	v_fma_f32 v153, |v105|, v81, v153
	v_fma_f32 v154, |v106|, v81, v154
	v_fma_f32 v155, |v107|, v81, v155
	v_fma_f32 v156, |v108|, v81, v156
	v_fma_f32 v157, |v109|, v81, v157
	v_fma_f32 v158, |v110|, v81, v158
	v_fma_f32 v159, |v111|, v81, v159
	v_fma_f32 v160, |v112|, v81, v160
	v_fma_f32 v161, |v113|, v81, v161
	v_fma_f32 v98, |v114|, v81, v98
	v_fma_f32 v99, |v115|, v81, v99
	v_fma_f32 v100, |v116|, v81, v100
	v_fma_f32 v101, |v117|, v81, v101
	v_fma_f32 v102, |v118|, v81, v102
	v_fma_f32 v103, |v119|, v81, v103
	v_mfma_f32_32x32x16_bf16 v[136:151], v[44:47], v[240:243], 0
	v_mfma_f32_32x32x16_bf16 v[136:151], v[40:43], v[244:247], v[136:151]
	ds_read_b128 v[4:7], v216 offset:33632
	v_fma_f32 v152, |v120|, v82, v152
	v_fma_f32 v153, |v121|, v82, v153
	v_fma_f32 v154, |v122|, v82, v154
	v_fma_f32 v155, |v123|, v82, v155
	v_fma_f32 v156, |v124|, v82, v156
	v_fma_f32 v157, |v125|, v82, v157
	v_fma_f32 v158, |v126|, v82, v158
	v_fma_f32 v159, |v127|, v82, v159
	v_fma_f32 v160, |v128|, v82, v160
	v_fma_f32 v161, |v129|, v82, v161
	v_fma_f32 v98, |v130|, v82, v98
	v_fma_f32 v99, |v131|, v82, v99
	v_fma_f32 v100, |v132|, v82, v100
	v_fma_f32 v101, |v133|, v82, v101
	v_fma_f32 v102, |v134|, v82, v102
	v_fma_f32 v103, |v135|, v82, v103
	s_waitcnt lgkmcnt(0)
	v_mfma_f32_32x32x16_bf16 v[104:119], v[44:47], v[248:251], 0
	v_mfma_f32_32x32x16_bf16 v[104:119], v[40:43], v[4:7], v[104:119]
	ds_read_b128 v[8:11], v216 offset:33664
	ds_read_b128 v[12:15], v216 offset:33696
	v_fma_f32 v152, |v136|, v83, v152
	v_fma_f32 v153, |v137|, v83, v153
	v_fma_f32 v154, |v138|, v83, v154
	v_fma_f32 v155, |v139|, v83, v155
	v_fma_f32 v156, |v140|, v83, v156
	v_fma_f32 v157, |v141|, v83, v157
	v_fma_f32 v158, |v142|, v83, v158
	v_fma_f32 v159, |v143|, v83, v159
	v_fma_f32 v160, |v144|, v83, v160
	v_fma_f32 v161, |v145|, v83, v161
	v_fma_f32 v98, |v146|, v83, v98
	v_fma_f32 v99, |v147|, v83, v99
	v_fma_f32 v100, |v148|, v83, v100
	v_fma_f32 v101, |v149|, v83, v101
	v_fma_f32 v102, |v150|, v83, v102
	v_fma_f32 v103, |v151|, v83, v103
	s_waitcnt lgkmcnt(0)
	v_mfma_f32_32x32x16_bf16 v[120:135], v[44:47], v[8:11], 0
	v_mfma_f32_32x32x16_bf16 v[120:135], v[40:43], v[12:15], v[120:135]
	ds_read_b128 v[0:3], v216 offset:33728
	ds_read_b128 v[4:7], v216 offset:33760
	v_fma_f32 v152, |v104|, v84, v152
	v_fma_f32 v153, |v105|, v84, v153
	v_fma_f32 v154, |v106|, v84, v154
	v_fma_f32 v155, |v107|, v84, v155
	v_fma_f32 v156, |v108|, v84, v156
	v_fma_f32 v157, |v109|, v84, v157
	v_fma_f32 v158, |v110|, v84, v158
	v_fma_f32 v159, |v111|, v84, v159
	v_fma_f32 v160, |v112|, v84, v160
	v_fma_f32 v161, |v113|, v84, v161
	v_fma_f32 v98, |v114|, v84, v98
	v_fma_f32 v99, |v115|, v84, v99
	v_fma_f32 v100, |v116|, v84, v100
	v_fma_f32 v101, |v117|, v84, v101
	v_fma_f32 v102, |v118|, v84, v102
	v_fma_f32 v103, |v119|, v84, v103
	s_waitcnt lgkmcnt(0)
	v_mfma_f32_32x32x16_bf16 v[136:151], v[44:47], v[0:3], 0
	v_mfma_f32_32x32x16_bf16 v[136:151], v[40:43], v[4:7], v[136:151]
	v_fma_f32 v152, |v120|, v85, v152
	v_fma_f32 v153, |v121|, v85, v153
	v_fma_f32 v154, |v122|, v85, v154
	v_fma_f32 v155, |v123|, v85, v155
	v_fma_f32 v156, |v124|, v85, v156
	v_fma_f32 v157, |v125|, v85, v157
	v_fma_f32 v158, |v126|, v85, v158
	v_fma_f32 v159, |v127|, v85, v159
	v_fma_f32 v160, |v128|, v85, v160
	v_fma_f32 v161, |v129|, v85, v161
	v_fma_f32 v98, |v130|, v85, v98
	v_fma_f32 v99, |v131|, v85, v99
	v_fma_f32 v100, |v132|, v85, v100
	v_fma_f32 v101, |v133|, v85, v101
	v_fma_f32 v102, |v134|, v85, v102
	v_fma_f32 v103, |v135|, v85, v103
	v_fma_f32 v40, |v136|, v86, v152
	v_fma_f32 v22, |v137|, v86, v153
	v_fma_f32 v21, |v138|, v86, v154
	v_fma_f32 v20, |v139|, v86, v155
	v_fma_f32 v19, |v140|, v86, v156
	v_fma_f32 v18, |v141|, v86, v157
	v_fma_f32 v17, |v142|, v86, v158
	v_fma_f32 v16, |v143|, v86, v159
	v_fma_f32 v7, |v144|, v86, v160
	v_fma_f32 v6, |v145|, v86, v161
	v_fma_f32 v5, |v146|, v86, v98
	v_fma_f32 v4, |v147|, v86, v99
	v_fma_f32 v3, |v148|, v86, v100
	v_fma_f32 v2, |v149|, v86, v101
	v_fma_f32 v1, |v150|, v86, v102
	v_fma_f32 v0, |v151|, v86, v103
	v_ashrrev_i32_e32 v8, 31, v40
	v_bitop3_b32 v8, v8, v40, s67 bitop3:0x36
	v_lshrrev_b32_e32 v9, s58, v8
	v_lshrrev_b32_e32 v8, 8, v9
	v_cmp_eq_u32_e64 s[52:53], v8, v94
	s_and_saveexec_b64 s[64:65], s[0:1]
	s_xor_b64 s[64:65], exec, s[64:65]
	s_cbranch_execnz .LBB0_271
	s_andn2_saveexec_b64 s[64:65], s[64:65]
	s_cbranch_execnz .LBB0_302

; DI void dsa_thr_item(const Params& p, int b, int qblk, char* smem) {
;     ...
;       } else {
; #pragma unroll
;         for (int i = 0; i < 16; ++i) {
;           unsigned ky = fkey(sc[i]);
;           unsigned hi = (ky >> shift);
;           if ((hi >> 8) == mypref) atomicAdd(&hist[(hi & 255u) * 32 + lr], 1u);
;         }
.LBB0_271:
	s_mov_b32 s101, 0
	s_cmp_lg_u32 s72, 0
	s_cbranch_scc1 .Lthr_h_gen
	v_lshl_add_u32 v136, v9, 7, v58
	v_mov_b32_e32 v152, 16
	v_ashrrev_i32_e32 v105, 31, v22
	v_ashrrev_i32_e32 v106, 31, v21
	v_ashrrev_i32_e32 v107, 31, v20
	v_bitop3_b32 v105, v105, v22, s67 bitop3:0x36
	v_bitop3_b32 v106, v106, v21, s67 bitop3:0x36
	v_bitop3_b32 v107, v107, v20, s67 bitop3:0x36
	v_lshrrev_b32_e32 v105, 24, v105
	v_lshrrev_b32_e32 v106, 24, v106
	v_lshrrev_b32_e32 v107, 24, v107
	v_lshl_add_u32 v137, v105, 7, v58
	v_lshl_add_u32 v138, v106, 7, v58
	v_lshl_add_u32 v139, v107, 7, v58
	v_cmp_ne_u32_e64 s[0:1], v105, v9
	v_cmp_ne_u32_e64 s[6:7], v106, v9
	v_cmp_ne_u32_e64 s[8:9], v107, v9
	v_subb_co_u32_e64 v152, s[12:13], v152, 0, s[0:1]
	v_subb_co_u32_e64 v152, s[12:13], v152, 0, s[6:7]
	v_subb_co_u32_e64 v152, s[12:13], v152, 0, s[8:9]
	s_and_saveexec_b64 s[74:75], s[0:1]
	ds_add_u32 v137, v71
	s_mov_b64 exec, s[74:75]
	s_and_saveexec_b64 s[74:75], s[6:7]
	ds_add_u32 v138, v71
	s_mov_b64 exec, s[74:75]
	s_and_saveexec_b64 s[74:75], s[8:9]
	ds_add_u32 v139, v71
	s_mov_b64 exec, s[74:75]
	v_ashrrev_i32_e32 v108, 31, v19
	v_ashrrev_i32_e32 v109, 31, v18
	v_ashrrev_i32_e32 v110, 31, v17
	v_ashrrev_i32_e32 v111, 31, v16
	v_bitop3_b32 v108, v108, v19, s67 bitop3:0x36
	v_bitop3_b32 v109, v109, v18, s67 bitop3:0x36
	v_bitop3_b32 v110, v110, v17, s67 bitop3:0x36
	v_bitop3_b32 v111, v111, v16, s67 bitop3:0x36
	v_lshrrev_b32_e32 v108, 24, v108
	v_lshrrev_b32_e32 v109, 24, v109
	v_lshrrev_b32_e32 v110, 24, v110
	v_lshrrev_b32_e32 v111, 24, v111
	v_lshl_add_u32 v140, v108, 7, v58
	v_lshl_add_u32 v141, v109, 7, v58
	v_lshl_add_u32 v142, v110, 7, v58
	v_lshl_add_u32 v143, v111, 7, v58
	v_cmp_ne_u32_e64 s[0:1], v108, v9
	v_cmp_ne_u32_e64 s[6:7], v109, v9
	v_cmp_ne_u32_e64 s[8:9], v110, v9
	v_cmp_ne_u32_e64 s[10:11], v111, v9
	v_subb_co_u32_e64 v152, s[12:13], v152, 0, s[0:1]
	v_subb_co_u32_e64 v152, s[12:13], v152, 0, s[6:7]
	v_subb_co_u32_e64 v152, s[12:13], v152, 0, s[8:9]
	v_subb_co_u32_e64 v152, s[12:13], v152, 0, s[10:11]
	s_and_saveexec_b64 s[74:75], s[0:1]
	ds_add_u32 v140, v71
	s_mov_b64 exec, s[74:75]
	s_and_saveexec_b64 s[74:75], s[6:7]
	ds_add_u32 v141, v71
	s_mov_b64 exec, s[74:75]
	s_and_saveexec_b64 s[74:75], s[8:9]
	ds_add_u32 v142, v71
	s_mov_b64 exec, s[74:75]
	s_and_saveexec_b64 s[74:75], s[10:11]
	ds_add_u32 v143, v71
	s_mov_b64 exec, s[74:75]
	v_ashrrev_i32_e32 v112, 31, v7
	v_ashrrev_i32_e32 v113, 31, v6
	v_ashrrev_i32_e32 v114, 31, v5
	v_ashrrev_i32_e32 v115, 31, v4
	v_bitop3_b32 v112, v112, v7, s67 bitop3:0x36
	v_bitop3_b32 v113, v113, v6, s67 bitop3:0x36
	v_bitop3_b32 v114, v114, v5, s67 bitop3:0x36
	v_bitop3_b32 v115, v115, v4, s67 bitop3:0x36
	v_lshrrev_b32_e32 v112, 24, v112
	v_lshrrev_b32_e32 v113, 24, v113
	v_lshrrev_b32_e32 v114, 24, v114
	v_lshrrev_b32_e32 v115, 24, v115
	v_lshl_add_u32 v144, v112, 7, v58
	v_lshl_add_u32 v145, v113, 7, v58
	v_lshl_add_u32 v146, v114, 7, v58
	v_lshl_add_u32 v147, v115, 7, v58
	v_cmp_ne_u32_e64 s[0:1], v112, v9
	v_cmp_ne_u32_e64 s[6:7], v113, v9
	v_cmp_ne_u32_e64 s[8:9], v114, v9
	v_cmp_ne_u32_e64 s[10:11], v115, v9
	v_subb_co_u32_e64 v152, s[12:13], v152, 0, s[0:1]
	v_subb_co_u32_e64 v152, s[12:13], v152, 0, s[6:7]
	v_subb_co_u32_e64 v152, s[12:13], v152, 0, s[8:9]
	v_subb_co_u32_e64 v152, s[12:13], v152, 0, s[10:11]
	s_and_saveexec_b64 s[74:75], s[0:1]
	ds_add_u32 v144, v71
	s_mov_b64 exec, s[74:75]
	s_and_saveexec_b64 s[74:75], s[6:7]
	ds_add_u32 v145, v71
	s_mov_b64 exec, s[74:75]
	s_and_saveexec_b64 s[74:75], s[8:9]
	ds_add_u32 v146, v71
	s_mov_b64 exec, s[74:75]
	s_and_saveexec_b64 s[74:75], s[10:11]
	ds_add_u32 v147, v71
	s_mov_b64 exec, s[74:75]
	v_ashrrev_i32_e32 v116, 31, v3
	v_ashrrev_i32_e32 v117, 31, v2
	v_ashrrev_i32_e32 v118, 31, v1
	v_ashrrev_i32_e32 v119, 31, v0
	v_bitop3_b32 v116, v116, v3, s67 bitop3:0x36
	v_bitop3_b32 v117, v117, v2, s67 bitop3:0x36
	v_bitop3_b32 v118, v118, v1, s67 bitop3:0x36
	v_bitop3_b32 v119, v119, v0, s67 bitop3:0x36
	v_lshrrev_b32_e32 v116, 24, v116
	v_lshrrev_b32_e32 v117, 24, v117
	v_lshrrev_b32_e32 v118, 24, v118
	v_lshrrev_b32_e32 v119, 24, v119
	v_lshl_add_u32 v148, v116, 7, v58
	v_lshl_add_u32 v149, v117, 7, v58
	v_lshl_add_u32 v150, v118, 7, v58
	v_lshl_add_u32 v151, v119, 7, v58
	v_cmp_ne_u32_e64 s[0:1], v116, v9
	v_cmp_ne_u32_e64 s[6:7], v117, v9
	v_cmp_ne_u32_e64 s[8:9], v118, v9
	v_cmp_ne_u32_e64 s[10:11], v119, v9
	v_subb_co_u32_e64 v152, s[12:13], v152, 0, s[0:1]
	v_subb_co_u32_e64 v152, s[12:13], v152, 0, s[6:7]
	v_subb_co_u32_e64 v152, s[12:13], v152, 0, s[8:9]
	v_subb_co_u32_e64 v152, s[12:13], v152, 0, s[10:11]
	s_and_saveexec_b64 s[74:75], s[0:1]
	ds_add_u32 v148, v71
	s_mov_b64 exec, s[74:75]
	s_and_saveexec_b64 s[74:75], s[6:7]
	ds_add_u32 v149, v71
	s_mov_b64 exec, s[74:75]
	s_and_saveexec_b64 s[74:75], s[8:9]
	ds_add_u32 v150, v71
	s_mov_b64 exec, s[74:75]
	s_and_saveexec_b64 s[74:75], s[10:11]
	ds_add_u32 v151, v71
	s_mov_b64 exec, s[74:75]
	ds_add_u32 v136, v152
	s_branch .Lthr_h_done
; DI void dsa_thr_item(const Params& p, int b, int qblk, char* smem) {
;     ...
;       } else {
; #pragma unroll
;         for (int i = 0; i < 16; ++i) {
;           unsigned ky = fkey(sc[i]);
;           unsigned hi = (ky >> shift);
;           if ((hi >> 8) == mypref) atomicAdd(&hist[(hi & 255u) * 32 + lr], 1u);
;         }
.Lthr_h_gen:
	s_add_i32 s62, s58, 8
	v_lshrrev_b32_e32 v120, 8, v9
	v_and_b32_e32 v104, 0xff, v9
	v_ashrrev_i32_e32 v105, 31, v22
	v_ashrrev_i32_e32 v106, 31, v21
	v_ashrrev_i32_e32 v107, 31, v20
	v_bitop3_b32 v105, v105, v22, s67 bitop3:0x36
	v_bitop3_b32 v106, v106, v21, s67 bitop3:0x36
	v_bitop3_b32 v107, v107, v20, s67 bitop3:0x36
	v_lshrrev_b32_e32 v121, s62, v105
	v_lshrrev_b32_e32 v122, s62, v106
	v_lshrrev_b32_e32 v123, s62, v107
	v_cmp_eq_u32_e64 s[0:1], v120, v94
	v_cmp_eq_u32_e64 s[6:7], v121, v94
	v_cmp_eq_u32_e64 s[8:9], v122, v94
	v_cmp_eq_u32_e64 s[10:11], v123, v94
	s_or_b64 s[76:77], s[0:1], s[6:7]
	s_or_b64 s[84:85], s[8:9], s[10:11]
	s_or_b64 s[76:77], s[76:77], s[84:85]
	s_cbranch_scc0 .Lthr_g0_skip
	s_mov_b32 s101, 1
	v_bfe_u32 v105, v105, s58, 8
	v_bfe_u32 v106, v106, s58, 8
	v_bfe_u32 v107, v107, s58, 8
	v_lshl_add_u32 v136, v104, 7, v58
	v_lshl_add_u32 v137, v105, 7, v58
	v_lshl_add_u32 v138, v106, 7, v58
	v_lshl_add_u32 v139, v107, 7, v58
	s_and_saveexec_b64 s[74:75], s[0:1]
	ds_add_u32 v136, v71
	s_mov_b64 exec, s[74:75]
	s_and_saveexec_b64 s[74:75], s[6:7]
	ds_add_u32 v137, v71
	s_mov_b64 exec, s[74:75]
	s_and_saveexec_b64 s[74:75], s[8:9]
	ds_add_u32 v138, v71
	s_mov_b64 exec, s[74:75]
	s_and_saveexec_b64 s[74:75], s[10:11]
	ds_add_u32 v139, v71
	s_mov_b64 exec, s[74:75]
.Lthr_g0_skip:
	v_ashrrev_i32_e32 v108, 31, v19
	v_ashrrev_i32_e32 v109, 31, v18
	v_ashrrev_i32_e32 v110, 31, v17
	v_ashrrev_i32_e32 v111, 31, v16
	v_bitop3_b32 v108, v108, v19, s67 bitop3:0x36
	v_bitop3_b32 v109, v109, v18, s67 bitop3:0x36
	v_bitop3_b32 v110, v110, v17, s67 bitop3:0x36
	v_bitop3_b32 v111, v111, v16, s67 bitop3:0x36
	v_lshrrev_b32_e32 v124, s62, v108
	v_lshrrev_b32_e32 v125, s62, v109
	v_lshrrev_b32_e32 v126, s62, v110
	v_lshrrev_b32_e32 v127, s62, v111
	v_cmp_eq_u32_e64 s[0:1], v124, v94
	v_cmp_eq_u32_e64 s[6:7], v125, v94
	v_cmp_eq_u32_e64 s[8:9], v126, v94
	v_cmp_eq_u32_e64 s[10:11], v127, v94
	s_or_b64 s[76:77], s[0:1], s[6:7]
	s_or_b64 s[84:85], s[8:9], s[10:11]
	s_or_b64 s[76:77], s[76:77], s[84:85]
	s_cbranch_scc0 .Lthr_g1_skip
	s_mov_b32 s101, 1
	v_bfe_u32 v108, v108, s58, 8
	v_bfe_u32 v109, v109, s58, 8
	v_bfe_u32 v110, v110, s58, 8
	v_bfe_u32 v111, v111, s58, 8
	v_lshl_add_u32 v140, v108, 7, v58
	v_lshl_add_u32 v141, v109, 7, v58
	v_lshl_add_u32 v142, v110, 7, v58
	v_lshl_add_u32 v143, v111, 7, v58
	s_and_saveexec_b64 s[74:75], s[0:1]
	ds_add_u32 v140, v71
	s_mov_b64 exec, s[74:75]
	s_and_saveexec_b64 s[74:75], s[6:7]
	ds_add_u32 v141, v71
	s_mov_b64 exec, s[74:75]
	s_and_saveexec_b64 s[74:75], s[8:9]
	ds_add_u32 v142, v71
	s_mov_b64 exec, s[74:75]
	s_and_saveexec_b64 s[74:75], s[10:11]
	ds_add_u32 v143, v71
	s_mov_b64 exec, s[74:75]
.Lthr_g1_skip:
	v_ashrrev_i32_e32 v112, 31, v7
	v_ashrrev_i32_e32 v113, 31, v6
	v_ashrrev_i32_e32 v114, 31, v5
	v_ashrrev_i32_e32 v115, 31, v4
	v_bitop3_b32 v112, v112, v7, s67 bitop3:0x36
	v_bitop3_b32 v113, v113, v6, s67 bitop3:0x36
	v_bitop3_b32 v114, v114, v5, s67 bitop3:0x36
	v_bitop3_b32 v115, v115, v4, s67 bitop3:0x36
	v_lshrrev_b32_e32 v128, s62, v112
	v_lshrrev_b32_e32 v129, s62, v113
	v_lshrrev_b32_e32 v130, s62, v114
	v_lshrrev_b32_e32 v131, s62, v115
	v_cmp_eq_u32_e64 s[0:1], v128, v94
	v_cmp_eq_u32_e64 s[6:7], v129, v94
	v_cmp_eq_u32_e64 s[8:9], v130, v94
	v_cmp_eq_u32_e64 s[10:11], v131, v94
	s_or_b64 s[76:77], s[0:1], s[6:7]
	s_or_b64 s[84:85], s[8:9], s[10:11]
	s_or_b64 s[76:77], s[76:77], s[84:85]
	s_cbranch_scc0 .Lthr_g2_skip
	s_mov_b32 s101, 1
	v_bfe_u32 v112, v112, s58, 8
	v_bfe_u32 v113, v113, s58, 8
	v_bfe_u32 v114, v114, s58, 8
	v_bfe_u32 v115, v115, s58, 8
	v_lshl_add_u32 v144, v112, 7, v58
	v_lshl_add_u32 v145, v113, 7, v58
	v_lshl_add_u32 v146, v114, 7, v58
	v_lshl_add_u32 v147, v115, 7, v58
	s_and_saveexec_b64 s[74:75], s[0:1]
	ds_add_u32 v144, v71
	s_mov_b64 exec, s[74:75]
	s_and_saveexec_b64 s[74:75], s[6:7]
	ds_add_u32 v145, v71
	s_mov_b64 exec, s[74:75]
	s_and_saveexec_b64 s[74:75], s[8:9]
	ds_add_u32 v146, v71
	s_mov_b64 exec, s[74:75]
	s_and_saveexec_b64 s[74:75], s[10:11]
	ds_add_u32 v147, v71
	s_mov_b64 exec, s[74:75]
.Lthr_g2_skip:
	v_ashrrev_i32_e32 v116, 31, v3
	v_ashrrev_i32_e32 v117, 31, v2
	v_ashrrev_i32_e32 v118, 31, v1
	v_ashrrev_i32_e32 v119, 31, v0
	v_bitop3_b32 v116, v116, v3, s67 bitop3:0x36
	v_bitop3_b32 v117, v117, v2, s67 bitop3:0x36
	v_bitop3_b32 v118, v118, v1, s67 bitop3:0x36
	v_bitop3_b32 v119, v119, v0, s67 bitop3:0x36
	v_lshrrev_b32_e32 v132, s62, v116
	v_lshrrev_b32_e32 v133, s62, v117
	v_lshrrev_b32_e32 v134, s62, v118
	v_lshrrev_b32_e32 v135, s62, v119
	v_cmp_eq_u32_e64 s[0:1], v132, v94
	v_cmp_eq_u32_e64 s[6:7], v133, v94
	v_cmp_eq_u32_e64 s[8:9], v134, v94
	v_cmp_eq_u32_e64 s[10:11], v135, v94
	s_or_b64 s[76:77], s[0:1], s[6:7]
	s_or_b64 s[84:85], s[8:9], s[10:11]
	s_or_b64 s[76:77], s[76:77], s[84:85]
	s_cbranch_scc0 .Lthr_g3_skip
	s_mov_b32 s101, 1
	v_bfe_u32 v116, v116, s58, 8
	v_bfe_u32 v117, v117, s58, 8
	v_bfe_u32 v118, v118, s58, 8
	v_bfe_u32 v119, v119, s58, 8
	v_lshl_add_u32 v148, v116, 7, v58
	v_lshl_add_u32 v149, v117, 7, v58
	v_lshl_add_u32 v150, v118, 7, v58
	v_lshl_add_u32 v151, v119, 7, v58
	s_and_saveexec_b64 s[74:75], s[0:1]
	ds_add_u32 v148, v71
	s_mov_b64 exec, s[74:75]
	s_and_saveexec_b64 s[74:75], s[6:7]
	ds_add_u32 v149, v71
	s_mov_b64 exec, s[74:75]
	s_and_saveexec_b64 s[74:75], s[8:9]
	ds_add_u32 v150, v71
	s_mov_b64 exec, s[74:75]
	s_and_saveexec_b64 s[74:75], s[10:11]
	ds_add_u32 v151, v71
	s_mov_b64 exec, s[74:75]
.Lthr_g3_skip:
.Lthr_h_done:
	s_lshl_b32 s100, s101, s99
	s_or_b32 s98, s98, s100
	s_mov_b64 s[62:63], 0
	s_andn2_saveexec_b64 s[64:65], s[64:65]
	s_cbranch_execz .LBB0_270
